# v011 + scan loader: removed always-true row<64 exec predication around prefetch loads
# speedup vs baseline: 1.0017x; 1.0017x over previous
.LBB0_545:
	s_waitcnt vmcnt(0)
	v_lshlrev_b32_e32 v144, 4, v166
	v_lshlrev_b32_e32 v145, 3, v166
	v_and_b32_e32 v142, 0xf0, v144
	s_add_i32 s0, 0, 0x11400
	v_and_b32_e32 v134, 0xe0, v144
	v_and_b32_e32 v135, 8, v145
	v_ashrrev_i32_e32 v140, 4, v166
	v_add_u32_e32 v133, s0, v142
	v_add3_u32 v137, s59, v134, v135
	v_mul_lo_u32 v134, v140, s58
	v_add_u32_e32 v136, v133, v134
	v_add_u32_e32 v134, v137, v134
	ds_write2_b64 v134, v[6:7], v[8:9] offset1:2
	v_lshlrev_b32_e32 v134, 6, v166
	v_add_u32_e32 v139, 0x100, v166
	v_and_b32_e32 v134, 0xc0, v134
	v_ashrrev_i32_e32 v138, 4, v139
	v_add3_u32 v131, s36, v131, v134
	v_mul_lo_u32 v134, v138, s58
	ds_write_b128 v136, v[2:5]
	v_add_u32_e32 v136, v133, v134
	v_add_u32_e32 v134, v137, v134
	ds_write_b128 v131, v[10:13]
	ds_write_b128 v136, v[14:17]
	ds_write2_b64 v134, v[18:19], v[20:21] offset1:2
	ds_write_b128 v131, v[22:25] offset:16
	v_add_u32_e32 v134, 0x200, v166
	v_ashrrev_i32_e32 v136, 4, v134
	v_mul_lo_u32 v134, v136, s58
	v_add_u32_e32 v141, v133, v134
	v_add_u32_e32 v134, v137, v134
	ds_write_b128 v141, v[26:29]
	ds_write2_b64 v134, v[30:31], v[32:33] offset1:2
	ds_write_b128 v131, v[34:37] offset:32
	v_add_u32_e32 v134, 0x300, v166
	v_ashrrev_i32_e32 v134, 4, v134
	v_mul_lo_u32 v141, v134, s58
	v_add_u32_e32 v133, v133, v141
	ds_write_b128 v133, v[38:41]
	v_add_u32_e32 v133, v137, v141
	ds_write2_b64 v133, v[46:47], v[48:49] offset1:2
	ds_write_b128 v131, v[58:61] offset:48
	v_and_b32_e32 v131, 0x60, v144
	v_add3_u32 v133, s60, v131, v135
	v_add3_u32 v131, s65, v131, v135
	v_lshrrev_b32_e32 v135, 3, v166
	v_mul_lo_u32 v135, v135, s68
	v_add_u32_e32 v137, v133, v135
	v_add_u32_e32 v135, v131, v135
	ds_write2_b64 v135, v[70:71], v[72:73] offset1:2
	v_lshrrev_b32_e32 v135, 3, v139
	v_mul_lo_u32 v135, v135, s68
	v_add_u32_e32 v133, v133, v135
	v_add_u32_e32 v131, v131, v135
	v_cmp_gt_i32_e32 vcc, s33, v166
	ds_write2_b64 v137, v[62:63], v[64:65] offset1:2
	ds_write2_b64 v133, v[78:79], v[80:81] offset1:2
	ds_write2_b64 v131, v[82:83], v[84:85] offset1:2
	s_and_saveexec_b64 s[0:1], vcc
	v_lshl_add_u32 v131, v166, 2, 0
	v_add_u32_e32 v131, 0x22c00, v131
	ds_write_b32 v131, v202
	s_or_b64 exec, exec, s[0:1]
	s_add_i32 s17, s16, 1
	s_cmpk_gt_u32 s17, 0x7c
	s_cbranch_scc1 .LBB0_573
	v_mov_b32_e32 v10, v130
	v_mov_b32_e32 v11, v130
	v_mov_b32_e32 v143, v130
	s_add_u32 s18, s43, s14
	v_mov_b32_e32 v12, v130
	v_mov_b32_e32 v13, v130
	v_mov_b64_e32 v[2:3], v[10:11]
	v_mov_b64_e32 v[6:7], v[10:11]
	v_lshl_add_u64 v[58:59], s[90:91], 0, v[142:143]
	v_lshl_add_u64 v[60:61], s[70:71], 0, v[142:143]
	s_addc_u32 s19, 0, s15
	v_cmp_gt_i32_e32 vcc, 64, v140
	v_mov_b64_e32 v[4:5], v[12:13]
	v_mov_b64_e32 v[8:9], v[12:13]
	v_ashrrev_i32_e32 v141, 31, v140
	v_lshl_add_u64 v[2:3], s[18:19], 0, v[140:141]
	v_lshlrev_b64 v[2:3], 12, v[2:3]
	v_lshl_add_u64 v[2:3], v[2:3], 0, s[38:39]
	v_lshl_add_u64 v[6:7], v[60:61], 0, v[2:3]
	v_lshl_add_u64 v[2:3], v[58:59], 0, v[2:3]
	global_load_dwordx4 v[2:5], v[2:3], off
	s_nop 0
	global_load_dwordx4 v[6:9], v[6:7], off
.LBB0_550:
	v_lshlrev_b32_e32 v14, 2, v166
	v_ashrrev_i32_e32 v133, 31, v132
	v_and_b32_e32 v16, 12, v14
	v_lshl_add_u64 v[14:15], s[18:19], 0, v[132:133]
	v_lshlrev_b64 v[14:15], 13, v[14:15]
	v_lshl_add_u64 v[14:15], s[10:11], 0, v[14:15]
	s_mov_b64 s[0:1], 0x180000
	v_cmp_gt_i32_e32 vcc, 64, v132
	v_lshl_add_u64 v[62:63], v[14:15], 0, s[0:1]
	v_lshlrev_b32_e32 v64, 4, v16
	v_mov_b32_e32 v65, v130
	v_lshl_add_u64 v[10:11], v[62:63], 0, v[64:65]
	global_load_dwordx4 v[10:13], v[10:11], off
.LBB0_552:
	v_mov_b32_e32 v131, v130
	v_mov_b32_e32 v132, v130
	v_mov_b32_e32 v133, v130
	v_mov_b64_e32 v[14:15], v[130:131]
	v_mov_b64_e32 v[18:19], v[130:131]
	v_cmp_gt_i32_e64 s[6:7], 64, v138
	v_mov_b64_e32 v[16:17], v[132:133]
	v_mov_b64_e32 v[20:21], v[132:133]
	v_ashrrev_i32_e32 v139, 31, v138
	v_lshl_add_u64 v[14:15], s[18:19], 0, v[138:139]
	v_lshlrev_b64 v[14:15], 12, v[14:15]
	v_lshl_add_u64 v[14:15], v[14:15], 0, s[38:39]
	v_lshl_add_u64 v[18:19], v[60:61], 0, v[14:15]
	v_lshl_add_u64 v[14:15], v[58:59], 0, v[14:15]
	global_load_dwordx4 v[14:17], v[14:15], off
	s_nop 0
	global_load_dwordx4 v[18:21], v[18:19], off
.LBB0_554:
	v_mov_b64_e32 v[22:23], v[130:131]
	v_mov_b64_e32 v[24:25], v[132:133]
	v_mov_b32_e32 v65, v130
	v_lshl_add_u64 v[22:23], v[62:63], 0, v[64:65]
	global_load_dwordx4 v[22:25], v[22:23], off offset:16
.LBB0_556:
	v_mov_b32_e32 v131, v130
	v_mov_b32_e32 v132, v130
	v_mov_b32_e32 v133, v130
	v_mov_b64_e32 v[26:27], v[130:131]
	v_mov_b64_e32 v[30:31], v[130:131]
	v_cmp_gt_i32_e64 s[6:7], 64, v136
	v_mov_b64_e32 v[28:29], v[132:133]
	v_mov_b64_e32 v[32:33], v[132:133]
	v_ashrrev_i32_e32 v137, 31, v136
	v_lshl_add_u64 v[26:27], s[18:19], 0, v[136:137]
	v_lshlrev_b64 v[26:27], 12, v[26:27]
	v_lshl_add_u64 v[26:27], v[26:27], 0, s[38:39]
	v_lshl_add_u64 v[30:31], v[60:61], 0, v[26:27]
	v_lshl_add_u64 v[26:27], v[58:59], 0, v[26:27]
	global_load_dwordx4 v[26:29], v[26:27], off
	s_nop 0
	global_load_dwordx4 v[30:33], v[30:31], off
.LBB0_558:
	v_mov_b64_e32 v[34:35], v[130:131]
	v_mov_b64_e32 v[36:37], v[132:133]
	v_mov_b32_e32 v65, v130
	v_lshl_add_u64 v[34:35], v[62:63], 0, v[64:65]
	global_load_dwordx4 v[34:37], v[34:35], off offset:32
.LBB0_560:
	v_mov_b32_e32 v131, v130
	v_mov_b32_e32 v132, v130
	v_mov_b32_e32 v133, v130
	v_mov_b64_e32 v[38:39], v[130:131]
	v_mov_b64_e32 v[46:47], v[130:131]
	v_cmp_gt_i32_e64 s[6:7], 64, v134
	v_mov_b64_e32 v[40:41], v[132:133]
	v_mov_b64_e32 v[48:49], v[132:133]
	v_ashrrev_i32_e32 v135, 31, v134
	v_lshl_add_u64 v[38:39], s[18:19], 0, v[134:135]
	v_lshlrev_b64 v[38:39], 12, v[38:39]
	v_lshl_add_u64 v[38:39], v[38:39], 0, s[38:39]
	v_lshl_add_u64 v[46:47], v[60:61], 0, v[38:39]
	v_lshl_add_u64 v[38:39], v[58:59], 0, v[38:39]
	global_load_dwordx4 v[38:41], v[38:39], off
	s_nop 0
	global_load_dwordx4 v[46:49], v[46:47], off
.LBB0_562:
	v_mov_b64_e32 v[58:59], v[130:131]
	v_mov_b64_e32 v[60:61], v[132:133]
	v_mov_b32_e32 v65, v130
	v_lshl_add_u64 v[58:59], v[62:63], 0, v[64:65]
	global_load_dwordx4 v[58:61], v[58:59], off offset:48
.LBB0_564:
	s_lshl_b32 s0, s50, 5
	s_add_i32 s0, s0, s42
	v_and_b32_e32 v78, 0xffffffc0, v145
	s_add_i32 s2, s0, 0x60
	v_ashrrev_i32_e32 v79, 31, v78
	v_and_b32_e32 v80, 0x70, v144
	v_lshlrev_b64 v[62:63], 1, v[78:79]
	s_add_u32 s0, s92, s48
	v_or_b32_e32 v62, v62, v80
	s_addc_u32 s1, s93, s49
	v_lshl_add_u64 v[62:63], s[0:1], 0, v[62:63]
	v_add_u32_e32 v78, 0x800, v78
	v_add_co_u32_e32 v64, vcc, s66, v62
	v_ashrrev_i32_e32 v79, 31, v78
	s_nop 0
	v_addc_co_u32_e32 v65, vcc, 0, v63, vcc
	v_lshlrev_b64 v[78:79], 1, v[78:79]
	v_add_co_u32_e32 v70, vcc, 0x41400000, v62
	v_or_b32_e32 v78, v78, v80
	s_nop 0
	v_addc_co_u32_e32 v71, vcc, 0, v63, vcc
	v_lshl_add_u64 v[78:79], s[0:1], 0, v[78:79]
	v_add_co_u32_e32 v80, vcc, 0x3d000000, v78
	global_load_dwordx4 v[62:65], v[64:65], off
	s_nop 0
	global_load_dwordx4 v[70:73], v[70:71], off
	v_addc_co_u32_e32 v81, vcc, 0, v79, vcc
	v_add_co_u32_e32 v82, vcc, 0x41400000, v78
	s_nop 1
	v_addc_co_u32_e32 v83, vcc, 0, v79, vcc
	global_load_dwordx4 v[78:81], v[80:81], off
	s_nop 0
	global_load_dwordx4 v[82:85], v[82:83], off
	v_cmp_lt_i32_e32 vcc, 63, v166
	s_and_saveexec_b64 s[0:1], vcc
	s_xor_b64 s[0:1], exec, s[0:1]
	s_cbranch_execz .LBB0_570
	v_cmp_lt_u32_e32 vcc, s57, v166
	s_and_saveexec_b64 s[6:7], vcc
	s_xor_b64 s[6:7], exec, s[6:7]
	s_add_u32 s18, s92, s46
	s_addc_u32 s19, s93, s47
	s_or_saveexec_b64 s[6:7], s[6:7]
	v_mov_b64_e32 v[132:133], s[18:19]
	s_xor_b64 exec, exec, s[6:7]
	s_lshl_b64 s[18:19], s[2:3], 8
	s_add_u32 s18, s69, s18
	v_mov_b32_e32 v167, v130
	s_addc_u32 s19, s67, s19
	v_lshl_add_u64 v[132:133], v[166:167], 2, s[18:19]
	s_or_b64 exec, exec, s[6:7]

.LBB0_581:
	s_cmpk_gt_u32 s17, 0x7b
	s_cbranch_scc1 .LBB0_539
	v_lshlrev_b32_e32 v120, 4, v166
	v_and_b32_e32 v42, 0xf0, v120
	v_mov_b32_e32 v43, v130
	v_mov_b32_e32 v54, v130
	v_mov_b32_e32 v55, v130
	v_lshl_add_u64 v[110:111], s[90:91], 0, v[42:43]
	v_lshl_add_u64 v[112:113], s[70:71], 0, v[42:43]
	v_ashrrev_i32_e32 v66, 4, v166
	v_mov_b32_e32 v56, v130
	v_mov_b32_e32 v57, v130
	v_mov_b64_e32 v[42:43], v[54:55]
	v_mov_b64_e32 v[50:51], v[54:55]
	v_cmp_gt_i32_e32 vcc, 64, v66
	v_mov_b64_e32 v[44:45], v[56:57]
	v_mov_b64_e32 v[52:53], v[56:57]
	v_ashrrev_i32_e32 v67, 31, v66
	v_lshl_add_u64 v[42:43], v[194:195], 0, v[66:67]
	v_lshlrev_b64 v[42:43], 12, v[42:43]
	v_lshl_add_u64 v[42:43], v[42:43], 0, s[62:63]
	v_lshl_add_u64 v[50:51], v[112:113], 0, v[42:43]
	v_lshl_add_u64 v[42:43], v[110:111], 0, v[42:43]
	global_load_dwordx4 v[42:45], v[42:43], off
	s_nop 0
	global_load_dwordx4 v[50:53], v[50:51], off
.LBB0_584:
	v_lshlrev_b32_e32 v66, 2, v166
	v_ashrrev_i32_e32 v169, 31, v168
	v_and_b32_e32 v68, 12, v66
	v_lshl_add_u64 v[66:67], v[194:195], 0, v[168:169]
	v_lshlrev_b64 v[66:67], 13, v[66:67]
	v_lshl_add_u64 v[66:67], s[10:11], 0, v[66:67]
	s_mov_b64 s[0:1], 0x200000
	v_lshl_add_u64 v[114:115], v[66:67], 0, s[0:1]
	v_lshlrev_b32_e32 v116, 4, v68
	v_mov_b32_e32 v117, v130
	v_lshl_add_u64 v[54:55], v[114:115], 0, v[116:117]
	global_load_dwordx4 v[54:57], v[54:55], off
.LBB0_586:
	v_add_u32_e32 v66, 0x100, v166
	v_mov_b32_e32 v131, v130
	v_ashrrev_i32_e32 v86, 4, v66
	v_mov_b32_e32 v132, v130
	v_mov_b32_e32 v133, v130
	v_mov_b64_e32 v[66:67], v[130:131]
	v_mov_b64_e32 v[74:75], v[130:131]
	v_cmp_gt_i32_e32 vcc, 64, v86
	v_mov_b64_e32 v[68:69], v[132:133]
	v_mov_b64_e32 v[76:77], v[132:133]
	v_ashrrev_i32_e32 v87, 31, v86
	v_lshl_add_u64 v[66:67], v[194:195], 0, v[86:87]
	v_lshlrev_b64 v[66:67], 12, v[66:67]
	v_lshl_add_u64 v[66:67], v[66:67], 0, s[62:63]
	v_lshl_add_u64 v[74:75], v[112:113], 0, v[66:67]
	v_lshl_add_u64 v[66:67], v[110:111], 0, v[66:67]
	global_load_dwordx4 v[66:69], v[66:67], off
	s_nop 0
	global_load_dwordx4 v[74:77], v[74:75], off
.LBB0_588:
	v_mov_b64_e32 v[86:87], v[130:131]
	v_mov_b64_e32 v[88:89], v[132:133]
	v_mov_b32_e32 v117, v130
	v_lshl_add_u64 v[86:87], v[114:115], 0, v[116:117]
	global_load_dwordx4 v[86:89], v[86:87], off offset:16
.LBB0_590:
	v_add_u32_e32 v90, 0x200, v166
	v_mov_b32_e32 v131, v130
	v_ashrrev_i32_e32 v98, 4, v90
	v_mov_b32_e32 v132, v130
	v_mov_b32_e32 v133, v130
	v_mov_b64_e32 v[90:91], v[130:131]
	v_mov_b64_e32 v[94:95], v[130:131]
	v_cmp_gt_i32_e32 vcc, 64, v98
	v_mov_b64_e32 v[92:93], v[132:133]
	v_mov_b64_e32 v[96:97], v[132:133]
	v_ashrrev_i32_e32 v99, 31, v98
	v_lshl_add_u64 v[90:91], v[194:195], 0, v[98:99]
	v_lshlrev_b64 v[90:91], 12, v[90:91]
	v_lshl_add_u64 v[90:91], v[90:91], 0, s[62:63]
	v_lshl_add_u64 v[94:95], v[112:113], 0, v[90:91]
	v_lshl_add_u64 v[90:91], v[110:111], 0, v[90:91]
	global_load_dwordx4 v[90:93], v[90:91], off
	s_nop 0
	global_load_dwordx4 v[94:97], v[94:95], off
.LBB0_592:
	v_mov_b64_e32 v[98:99], v[130:131]
	v_mov_b64_e32 v[100:101], v[132:133]
	v_mov_b32_e32 v117, v130
	v_lshl_add_u64 v[98:99], v[114:115], 0, v[116:117]
	global_load_dwordx4 v[98:101], v[98:99], off offset:32
.LBB0_594:
	v_add_u32_e32 v102, 0x300, v166
	v_mov_b32_e32 v131, v130
	v_ashrrev_i32_e32 v118, 4, v102
	v_mov_b32_e32 v132, v130
	v_mov_b32_e32 v133, v130
	v_mov_b64_e32 v[102:103], v[130:131]
	v_mov_b64_e32 v[106:107], v[130:131]
	v_cmp_gt_i32_e32 vcc, 64, v118
	v_mov_b64_e32 v[104:105], v[132:133]
	v_mov_b64_e32 v[108:109], v[132:133]
	v_ashrrev_i32_e32 v119, 31, v118
	v_lshl_add_u64 v[102:103], v[194:195], 0, v[118:119]
	v_lshlrev_b64 v[102:103], 12, v[102:103]
	v_lshl_add_u64 v[102:103], v[102:103], 0, s[62:63]
	v_lshl_add_u64 v[106:107], v[112:113], 0, v[102:103]
	v_lshl_add_u64 v[102:103], v[110:111], 0, v[102:103]
	global_load_dwordx4 v[102:105], v[102:103], off
	s_nop 0
	global_load_dwordx4 v[106:109], v[106:107], off
.LBB0_596:
	v_mov_b64_e32 v[110:111], v[130:131]
	v_mov_b64_e32 v[112:113], v[132:133]
	v_mov_b32_e32 v117, v130
	v_lshl_add_u64 v[110:111], v[114:115], 0, v[116:117]
	global_load_dwordx4 v[110:113], v[110:111], off offset:48
.LBB0_598:
	v_lshlrev_b32_e32 v114, 3, v166
	s_lshl_b32 s0, s50, 5
	s_add_i32 s0, s0, s42
	v_and_b32_e32 v122, 0xffffffc0, v114
	s_add_i32 s2, s0, 0x80
	v_ashrrev_i32_e32 v123, 31, v122
	v_and_b32_e32 v124, 0x70, v120
	v_lshlrev_b64 v[114:115], 1, v[122:123]
	s_add_u32 s0, s92, s28
	v_or_b32_e32 v114, v114, v124
	s_addc_u32 s1, s93, s29
	v_lshl_add_u64 v[114:115], s[0:1], 0, v[114:115]
	v_add_u32_e32 v122, 0x800, v122
	v_add_co_u32_e32 v116, vcc, s66, v114
	v_ashrrev_i32_e32 v123, 31, v122
	s_nop 0
	v_addc_co_u32_e32 v117, vcc, 0, v115, vcc
	v_lshlrev_b64 v[122:123], 1, v[122:123]
	v_add_co_u32_e32 v118, vcc, 0x41400000, v114
	v_or_b32_e32 v122, v122, v124
	s_nop 0
	v_addc_co_u32_e32 v119, vcc, 0, v115, vcc
	v_lshl_add_u64 v[122:123], s[0:1], 0, v[122:123]
	v_add_co_u32_e32 v124, vcc, 0x3d000000, v122
	global_load_dwordx4 v[114:117], v[116:117], off
	s_nop 0
	global_load_dwordx4 v[118:121], v[118:119], off
	v_addc_co_u32_e32 v125, vcc, 0, v123, vcc
	v_add_co_u32_e32 v126, vcc, 0x41400000, v122
	s_nop 1
	v_addc_co_u32_e32 v127, vcc, 0, v123, vcc
	global_load_dwordx4 v[122:125], v[124:125], off
	s_nop 0
	global_load_dwordx4 v[126:129], v[126:127], off
	v_cmp_lt_i32_e32 vcc, 63, v166
	s_and_saveexec_b64 s[0:1], vcc
	s_xor_b64 s[0:1], exec, s[0:1]
	s_cbranch_execz .LBB0_604
	v_cmp_lt_u32_e32 vcc, s57, v166
	s_and_saveexec_b64 s[6:7], vcc
	s_xor_b64 s[6:7], exec, s[6:7]
	s_add_u32 s18, s92, s44
	s_addc_u32 s19, s93, s45
	s_or_saveexec_b64 s[6:7], s[6:7]
	v_mov_b64_e32 v[132:133], s[18:19]
	s_xor_b64 exec, exec, s[6:7]
	s_lshl_b64 s[18:19], s[2:3], 8
	s_add_u32 s18, s69, s18
	v_mov_b32_e32 v167, v130
	s_addc_u32 s19, s67, s19
	v_lshl_add_u64 v[132:133], v[166:167], 2, s[18:19]
	s_or_b64 exec, exec, s[6:7]
